# scan pass 2 main loop: 4 time steps of loads in flight instead of 8 (gentler beside the attention items of the co-resident workgroup)
# baseline (speedup 1.0000x reference)
; DEV unsigned pack2(float a, float b) { float2v v = {a, b}; return __builtin_bit_cast(unsigned, __builtin_convertvector(v, bf16x2v)); }
; DEV float bflo(unsigned u) { return __uint_as_float(u << 16); }
; DEV float bfhi(unsigned u) { return __uint_as_float(u & 0xffff0000u); }
; DEV float gelu_exact(float v) { return 0.5f * v * (1.f + erff(v * 0.7071067811865476f)); }
; DEV void ph_scan2(const Params& p, int item) {
;     ...
; #pragma unroll 8
;   for (int t = 0; t < CHL; ++t) {
;     float4 a = *(const float4*)(p.a_arr + (row0 + t) * 1024 + ch);
;     float4 bb = *(const float4*)(p.b_arr + (row0 + t) * 1024 + ch);
;     u32x2 xg = *(const u32x2*)(p.z + (row0 + t) * ZLD + CXG + ch);
;     H[0] = a.x * H[0] + bb.x; H[1] = a.y * H[1] + bb.y; H[2] = a.z * H[2] + bb.z; H[3] = a.w * H[3] + bb.w;
;     u32x2 pk;
;     pk[0] = pack2(gelu_exact(bflo(xg[0])) * H[0], gelu_exact(bfhi(xg[0])) * H[1]);
;     pk[1] = pack2(gelu_exact(bflo(xg[1])) * H[2], gelu_exact(bfhi(xg[1])) * H[3]);
;     *(u32x2*)(p.orn + (row0 + t) * 1024 + ch) = pk;
;   }
.Lsc_main:
	global_load_dwordx4 v[80:83], v1, s[2:3]
	global_load_dwordx4 v[84:87], v1, s[4:5]
	global_load_dwordx2 v[88:89], v2, s[6:7]
	s_add_u32 s2, s2, 0x1000
	s_addc_u32 s3, s3, 0
	s_add_u32 s4, s4, 0x1000
	s_addc_u32 s5, s5, 0
	s_add_u32 s6, s6, 0x2500
	s_addc_u32 s7, s7, 0
	global_load_dwordx4 v[90:93], v1, s[2:3]
	global_load_dwordx4 v[94:97], v1, s[4:5]
	global_load_dwordx2 v[98:99], v2, s[6:7]
	s_add_u32 s2, s2, 0x1000
	s_addc_u32 s3, s3, 0
	s_add_u32 s4, s4, 0x1000
	s_addc_u32 s5, s5, 0
	s_add_u32 s6, s6, 0x2500
	s_addc_u32 s7, s7, 0
	global_load_dwordx4 v[100:103], v1, s[2:3]
	global_load_dwordx4 v[104:107], v1, s[4:5]
	global_load_dwordx2 v[108:109], v2, s[6:7]
	s_add_u32 s2, s2, 0x1000
	s_addc_u32 s3, s3, 0
	s_add_u32 s4, s4, 0x1000
	s_addc_u32 s5, s5, 0
	s_add_u32 s6, s6, 0x2500
	s_addc_u32 s7, s7, 0
	global_load_dwordx4 v[110:113], v1, s[2:3]
	global_load_dwordx4 v[114:117], v1, s[4:5]
	global_load_dwordx2 v[118:119], v2, s[6:7]
	s_add_u32 s2, s2, 0x1000
	s_addc_u32 s3, s3, 0
	s_add_u32 s4, s4, 0x1000
	s_addc_u32 s5, s5, 0
	s_add_u32 s6, s6, 0x2500
	s_addc_u32 s7, s7, 0
	s_waitcnt vmcnt(9)
	v_fma_f32 v4, v80, v4, v84
	v_fma_f32 v5, v81, v5, v85
	v_fma_f32 v6, v82, v6, v86
	v_fma_f32 v7, v83, v7, v87
	v_lshlrev_b32_e32 v168, 16, v88
	v_and_b32_e32 v169, 0xffff0000, v88
	v_lshlrev_b32_e32 v170, 16, v89
	v_and_b32_e32 v171, 0xffff0000, v89
	v_mul_f32_e32 v160, 0x3f3504f3, v168
	v_mul_f32_e32 v161, v160, v160
	v_fmamk_f32 v162, v161, 0xba1345e1, v8
	v_fmaak_f32 v162, v161, v162, 0xbcdac9b8
	v_fmaak_f32 v162, v161, v162, 0x3de703be
	v_fmaak_f32 v162, v161, v162, 0xbec09330
	v_fmaak_f32 v161, v161, v162, 0x3e0375d0
	v_fma_f32 v165, |v160|, v161, |v160|
	v_fma_f32 v161, |v160|, s72, v9
	v_fma_f32 v161, |v160|, v161, s73
	v_fma_f32 v161, |v160|, v161, s74
	v_fma_f32 v161, |v160|, v161, s75
	v_fma_f32 v161, |v160|, v161, s76
	v_fma_f32 v161, |v160|, v161, s77
	v_fma_f32 v161, |v160|, v161, |v160|
	v_mul_f32_e32 v162, 0xbfb8aa3b, v161
	v_fma_f32 v163, v161, s78, -v162
	v_rndne_f32_e32 v164, v162
	v_fmac_f32_e32 v163, 0xb2a5705f, v161
	v_sub_f32_e32 v162, v162, v164
	v_add_f32_e32 v162, v162, v163
	v_cvt_i32_f32_e32 v163, v164
	v_exp_f32_e32 v162, v162
	v_cmp_nlt_f32_e32 vcc, s79, v161
	v_ldexp_f32 v162, v162, v163
	s_nop 0
	v_cndmask_b32_e32 v162, 0, v162, vcc
	v_cmp_ngt_f32_e32 vcc, s80, v161
	s_nop 1
	v_cndmask_b32_e32 v161, v3, v162, vcc
	v_sub_f32_e32 v166, 1.0, v161
	v_cmp_lt_f32_e64 vcc, |v160|, 1.0
	s_nop 1
	v_cndmask_b32_e32 v165, v166, v165, vcc
	v_bfi_b32 v165, s81, v165, v160
	v_mul_f32_e32 v161, 0.5, v168
	v_add_f32_e32 v165, 1.0, v165
	v_mul_f32_e32 v161, v161, v165
	v_mul_f32_e32 v176, v161, v4
	v_mul_f32_e32 v160, 0x3f3504f3, v169
	v_mul_f32_e32 v161, v160, v160
	v_fmamk_f32 v162, v161, 0xba1345e1, v8
	v_fmaak_f32 v162, v161, v162, 0xbcdac9b8
	v_fmaak_f32 v162, v161, v162, 0x3de703be
	v_fmaak_f32 v162, v161, v162, 0xbec09330
	v_fmaak_f32 v161, v161, v162, 0x3e0375d0
	v_fma_f32 v165, |v160|, v161, |v160|
	v_fma_f32 v161, |v160|, s72, v9
	v_fma_f32 v161, |v160|, v161, s73
	v_fma_f32 v161, |v160|, v161, s74
	v_fma_f32 v161, |v160|, v161, s75
	v_fma_f32 v161, |v160|, v161, s76
	v_fma_f32 v161, |v160|, v161, s77
	v_fma_f32 v161, |v160|, v161, |v160|
	v_mul_f32_e32 v162, 0xbfb8aa3b, v161
	v_fma_f32 v163, v161, s78, -v162
	v_rndne_f32_e32 v164, v162
	v_fmac_f32_e32 v163, 0xb2a5705f, v161
	v_sub_f32_e32 v162, v162, v164
	v_add_f32_e32 v162, v162, v163
	v_cvt_i32_f32_e32 v163, v164
	v_exp_f32_e32 v162, v162
	v_cmp_nlt_f32_e32 vcc, s79, v161
	v_ldexp_f32 v162, v162, v163
	s_nop 0
	v_cndmask_b32_e32 v162, 0, v162, vcc
	v_cmp_ngt_f32_e32 vcc, s80, v161
	s_nop 1
	v_cndmask_b32_e32 v161, v3, v162, vcc
	v_sub_f32_e32 v166, 1.0, v161
	v_cmp_lt_f32_e64 vcc, |v160|, 1.0
	s_nop 1
	v_cndmask_b32_e32 v165, v166, v165, vcc
	v_bfi_b32 v165, s81, v165, v160
	v_mul_f32_e32 v161, 0.5, v169
	v_add_f32_e32 v165, 1.0, v165
	v_mul_f32_e32 v161, v161, v165
	v_mul_f32_e32 v177, v161, v5
	v_mul_f32_e32 v160, 0x3f3504f3, v170
	v_mul_f32_e32 v161, v160, v160
	v_fmamk_f32 v162, v161, 0xba1345e1, v8
	v_fmaak_f32 v162, v161, v162, 0xbcdac9b8
	v_fmaak_f32 v162, v161, v162, 0x3de703be
	v_fmaak_f32 v162, v161, v162, 0xbec09330
	v_fmaak_f32 v161, v161, v162, 0x3e0375d0
	v_fma_f32 v165, |v160|, v161, |v160|
	v_fma_f32 v161, |v160|, s72, v9
	v_fma_f32 v161, |v160|, v161, s73
	v_fma_f32 v161, |v160|, v161, s74
	v_fma_f32 v161, |v160|, v161, s75
	v_fma_f32 v161, |v160|, v161, s76
	v_fma_f32 v161, |v160|, v161, s77
	v_fma_f32 v161, |v160|, v161, |v160|
	v_mul_f32_e32 v162, 0xbfb8aa3b, v161
	v_fma_f32 v163, v161, s78, -v162
	v_rndne_f32_e32 v164, v162
	v_fmac_f32_e32 v163, 0xb2a5705f, v161
	v_sub_f32_e32 v162, v162, v164
	v_add_f32_e32 v162, v162, v163
	v_cvt_i32_f32_e32 v163, v164
	v_exp_f32_e32 v162, v162
	v_cmp_nlt_f32_e32 vcc, s79, v161
	v_ldexp_f32 v162, v162, v163
	s_nop 0
	v_cndmask_b32_e32 v162, 0, v162, vcc
	v_cmp_ngt_f32_e32 vcc, s80, v161
	s_nop 1
	v_cndmask_b32_e32 v161, v3, v162, vcc
	v_sub_f32_e32 v166, 1.0, v161
	v_cmp_lt_f32_e64 vcc, |v160|, 1.0
	s_nop 1
	v_cndmask_b32_e32 v165, v166, v165, vcc
	v_bfi_b32 v165, s81, v165, v160
	v_mul_f32_e32 v161, 0.5, v170
	v_add_f32_e32 v165, 1.0, v165
	v_mul_f32_e32 v161, v161, v165
	v_mul_f32_e32 v178, v161, v6
	v_mul_f32_e32 v160, 0x3f3504f3, v171
	v_mul_f32_e32 v161, v160, v160
	v_fmamk_f32 v162, v161, 0xba1345e1, v8
	v_fmaak_f32 v162, v161, v162, 0xbcdac9b8
	v_fmaak_f32 v162, v161, v162, 0x3de703be
	v_fmaak_f32 v162, v161, v162, 0xbec09330
	v_fmaak_f32 v161, v161, v162, 0x3e0375d0
	v_fma_f32 v165, |v160|, v161, |v160|
	v_fma_f32 v161, |v160|, s72, v9
	v_fma_f32 v161, |v160|, v161, s73
	v_fma_f32 v161, |v160|, v161, s74
	v_fma_f32 v161, |v160|, v161, s75
	v_fma_f32 v161, |v160|, v161, s76
	v_fma_f32 v161, |v160|, v161, s77
	v_fma_f32 v161, |v160|, v161, |v160|
	v_mul_f32_e32 v162, 0xbfb8aa3b, v161
	v_fma_f32 v163, v161, s78, -v162
	v_rndne_f32_e32 v164, v162
	v_fmac_f32_e32 v163, 0xb2a5705f, v161
	v_sub_f32_e32 v162, v162, v164
	v_add_f32_e32 v162, v162, v163
	v_cvt_i32_f32_e32 v163, v164
	v_exp_f32_e32 v162, v162
	v_cmp_nlt_f32_e32 vcc, s79, v161
	v_ldexp_f32 v162, v162, v163
	s_nop 0
	v_cndmask_b32_e32 v162, 0, v162, vcc
	v_cmp_ngt_f32_e32 vcc, s80, v161
	s_nop 1
	v_cndmask_b32_e32 v161, v3, v162, vcc
	v_sub_f32_e32 v166, 1.0, v161
	v_cmp_lt_f32_e64 vcc, |v160|, 1.0
	s_nop 1
	v_cndmask_b32_e32 v165, v166, v165, vcc
	v_bfi_b32 v165, s81, v165, v160
	v_mul_f32_e32 v161, 0.5, v171
	v_add_f32_e32 v165, 1.0, v165
	v_mul_f32_e32 v161, v161, v165
	v_mul_f32_e32 v179, v161, v7
	v_cvt_pk_bf16_f32 v180, v176, v177
	v_cvt_pk_bf16_f32 v181, v178, v179
	global_store_dwordx2 v2, v[180:181], s[34:35]
	s_add_u32 s34, s34, 0x800
	s_addc_u32 s35, s35, 0
	s_waitcnt vmcnt(7)
; DEV unsigned pack2(float a, float b) { float2v v = {a, b}; return __builtin_bit_cast(unsigned, __builtin_convertvector(v, bf16x2v)); }
; DEV float bflo(unsigned u) { return __uint_as_float(u << 16); }
; DEV float bfhi(unsigned u) { return __uint_as_float(u & 0xffff0000u); }
; DEV float gelu_exact(float v) { return 0.5f * v * (1.f + erff(v * 0.7071067811865476f)); }
; DEV void ph_scan2(const Params& p, int item) {
;     ...
; #pragma unroll 8
;   for (int t = 0; t < CHL; ++t) {
;     float4 a = *(const float4*)(p.a_arr + (row0 + t) * 1024 + ch);
;     float4 bb = *(const float4*)(p.b_arr + (row0 + t) * 1024 + ch);
;     u32x2 xg = *(const u32x2*)(p.z + (row0 + t) * ZLD + CXG + ch);
;     H[0] = a.x * H[0] + bb.x; H[1] = a.y * H[1] + bb.y; H[2] = a.z * H[2] + bb.z; H[3] = a.w * H[3] + bb.w;
;     u32x2 pk;
;     pk[0] = pack2(gelu_exact(bflo(xg[0])) * H[0], gelu_exact(bfhi(xg[0])) * H[1]);
;     pk[1] = pack2(gelu_exact(bflo(xg[1])) * H[2], gelu_exact(bfhi(xg[1])) * H[3]);
;     *(u32x2*)(p.orn + (row0 + t) * 1024 + ch) = pk;
;   }
	v_fma_f32 v4, v90, v4, v94
	v_fma_f32 v5, v91, v5, v95
	v_fma_f32 v6, v92, v6, v96
	v_fma_f32 v7, v93, v7, v97
	v_lshlrev_b32_e32 v168, 16, v98
	v_and_b32_e32 v169, 0xffff0000, v98
	v_lshlrev_b32_e32 v170, 16, v99
	v_and_b32_e32 v171, 0xffff0000, v99
	v_mul_f32_e32 v160, 0x3f3504f3, v168
	v_mul_f32_e32 v161, v160, v160
	v_fmamk_f32 v162, v161, 0xba1345e1, v8
	v_fmaak_f32 v162, v161, v162, 0xbcdac9b8
	v_fmaak_f32 v162, v161, v162, 0x3de703be
	v_fmaak_f32 v162, v161, v162, 0xbec09330
	v_fmaak_f32 v161, v161, v162, 0x3e0375d0
	v_fma_f32 v165, |v160|, v161, |v160|
	v_fma_f32 v161, |v160|, s72, v9
	v_fma_f32 v161, |v160|, v161, s73
	v_fma_f32 v161, |v160|, v161, s74
	v_fma_f32 v161, |v160|, v161, s75
	v_fma_f32 v161, |v160|, v161, s76
	v_fma_f32 v161, |v160|, v161, s77
	v_fma_f32 v161, |v160|, v161, |v160|
	v_mul_f32_e32 v162, 0xbfb8aa3b, v161
	v_fma_f32 v163, v161, s78, -v162
	v_rndne_f32_e32 v164, v162
	v_fmac_f32_e32 v163, 0xb2a5705f, v161
	v_sub_f32_e32 v162, v162, v164
	v_add_f32_e32 v162, v162, v163
	v_cvt_i32_f32_e32 v163, v164
	v_exp_f32_e32 v162, v162
	v_cmp_nlt_f32_e32 vcc, s79, v161
	v_ldexp_f32 v162, v162, v163
	s_nop 0
	v_cndmask_b32_e32 v162, 0, v162, vcc
	v_cmp_ngt_f32_e32 vcc, s80, v161
	s_nop 1
	v_cndmask_b32_e32 v161, v3, v162, vcc
	v_sub_f32_e32 v166, 1.0, v161
	v_cmp_lt_f32_e64 vcc, |v160|, 1.0
	s_nop 1
	v_cndmask_b32_e32 v165, v166, v165, vcc
	v_bfi_b32 v165, s81, v165, v160
	v_mul_f32_e32 v161, 0.5, v168
	v_add_f32_e32 v165, 1.0, v165
	v_mul_f32_e32 v161, v161, v165
	v_mul_f32_e32 v176, v161, v4
	v_mul_f32_e32 v160, 0x3f3504f3, v169
	v_mul_f32_e32 v161, v160, v160
	v_fmamk_f32 v162, v161, 0xba1345e1, v8
	v_fmaak_f32 v162, v161, v162, 0xbcdac9b8
	v_fmaak_f32 v162, v161, v162, 0x3de703be
	v_fmaak_f32 v162, v161, v162, 0xbec09330
	v_fmaak_f32 v161, v161, v162, 0x3e0375d0
	v_fma_f32 v165, |v160|, v161, |v160|
	v_fma_f32 v161, |v160|, s72, v9
	v_fma_f32 v161, |v160|, v161, s73
	v_fma_f32 v161, |v160|, v161, s74
	v_fma_f32 v161, |v160|, v161, s75
	v_fma_f32 v161, |v160|, v161, s76
	v_fma_f32 v161, |v160|, v161, s77
	v_fma_f32 v161, |v160|, v161, |v160|
	v_mul_f32_e32 v162, 0xbfb8aa3b, v161
	v_fma_f32 v163, v161, s78, -v162
	v_rndne_f32_e32 v164, v162
	v_fmac_f32_e32 v163, 0xb2a5705f, v161
	v_sub_f32_e32 v162, v162, v164
	v_add_f32_e32 v162, v162, v163
	v_cvt_i32_f32_e32 v163, v164
	v_exp_f32_e32 v162, v162
	v_cmp_nlt_f32_e32 vcc, s79, v161
	v_ldexp_f32 v162, v162, v163
	s_nop 0
	v_cndmask_b32_e32 v162, 0, v162, vcc
	v_cmp_ngt_f32_e32 vcc, s80, v161
	s_nop 1
	v_cndmask_b32_e32 v161, v3, v162, vcc
	v_sub_f32_e32 v166, 1.0, v161
	v_cmp_lt_f32_e64 vcc, |v160|, 1.0
	s_nop 1
	v_cndmask_b32_e32 v165, v166, v165, vcc
	v_bfi_b32 v165, s81, v165, v160
	v_mul_f32_e32 v161, 0.5, v169
	v_add_f32_e32 v165, 1.0, v165
	v_mul_f32_e32 v161, v161, v165
	v_mul_f32_e32 v177, v161, v5
	v_mul_f32_e32 v160, 0x3f3504f3, v170
	v_mul_f32_e32 v161, v160, v160
	v_fmamk_f32 v162, v161, 0xba1345e1, v8
	v_fmaak_f32 v162, v161, v162, 0xbcdac9b8
	v_fmaak_f32 v162, v161, v162, 0x3de703be
	v_fmaak_f32 v162, v161, v162, 0xbec09330
	v_fmaak_f32 v161, v161, v162, 0x3e0375d0
	v_fma_f32 v165, |v160|, v161, |v160|
	v_fma_f32 v161, |v160|, s72, v9
	v_fma_f32 v161, |v160|, v161, s73
	v_fma_f32 v161, |v160|, v161, s74
	v_fma_f32 v161, |v160|, v161, s75
	v_fma_f32 v161, |v160|, v161, s76
	v_fma_f32 v161, |v160|, v161, s77
	v_fma_f32 v161, |v160|, v161, |v160|
	v_mul_f32_e32 v162, 0xbfb8aa3b, v161
	v_fma_f32 v163, v161, s78, -v162
	v_rndne_f32_e32 v164, v162
	v_fmac_f32_e32 v163, 0xb2a5705f, v161
	v_sub_f32_e32 v162, v162, v164
	v_add_f32_e32 v162, v162, v163
	v_cvt_i32_f32_e32 v163, v164
	v_exp_f32_e32 v162, v162
	v_cmp_nlt_f32_e32 vcc, s79, v161
	v_ldexp_f32 v162, v162, v163
	s_nop 0
	v_cndmask_b32_e32 v162, 0, v162, vcc
	v_cmp_ngt_f32_e32 vcc, s80, v161
	s_nop 1
	v_cndmask_b32_e32 v161, v3, v162, vcc
	v_sub_f32_e32 v166, 1.0, v161
	v_cmp_lt_f32_e64 vcc, |v160|, 1.0
	s_nop 1
	v_cndmask_b32_e32 v165, v166, v165, vcc
	v_bfi_b32 v165, s81, v165, v160
	v_mul_f32_e32 v161, 0.5, v170
	v_add_f32_e32 v165, 1.0, v165
	v_mul_f32_e32 v161, v161, v165
	v_mul_f32_e32 v178, v161, v6
	v_mul_f32_e32 v160, 0x3f3504f3, v171
	v_mul_f32_e32 v161, v160, v160
	v_fmamk_f32 v162, v161, 0xba1345e1, v8
	v_fmaak_f32 v162, v161, v162, 0xbcdac9b8
	v_fmaak_f32 v162, v161, v162, 0x3de703be
	v_fmaak_f32 v162, v161, v162, 0xbec09330
	v_fmaak_f32 v161, v161, v162, 0x3e0375d0
	v_fma_f32 v165, |v160|, v161, |v160|
	v_fma_f32 v161, |v160|, s72, v9
	v_fma_f32 v161, |v160|, v161, s73
	v_fma_f32 v161, |v160|, v161, s74
	v_fma_f32 v161, |v160|, v161, s75
	v_fma_f32 v161, |v160|, v161, s76
	v_fma_f32 v161, |v160|, v161, s77
	v_fma_f32 v161, |v160|, v161, |v160|
	v_mul_f32_e32 v162, 0xbfb8aa3b, v161
	v_fma_f32 v163, v161, s78, -v162
	v_rndne_f32_e32 v164, v162
	v_fmac_f32_e32 v163, 0xb2a5705f, v161
	v_sub_f32_e32 v162, v162, v164
	v_add_f32_e32 v162, v162, v163
	v_cvt_i32_f32_e32 v163, v164
	v_exp_f32_e32 v162, v162
	v_cmp_nlt_f32_e32 vcc, s79, v161
	v_ldexp_f32 v162, v162, v163
	s_nop 0
	v_cndmask_b32_e32 v162, 0, v162, vcc
	v_cmp_ngt_f32_e32 vcc, s80, v161
	s_nop 1
	v_cndmask_b32_e32 v161, v3, v162, vcc
	v_sub_f32_e32 v166, 1.0, v161
	v_cmp_lt_f32_e64 vcc, |v160|, 1.0
	s_nop 1
	v_cndmask_b32_e32 v165, v166, v165, vcc
	v_bfi_b32 v165, s81, v165, v160
	v_mul_f32_e32 v161, 0.5, v171
	v_add_f32_e32 v165, 1.0, v165
	v_mul_f32_e32 v161, v161, v165
	v_mul_f32_e32 v179, v161, v7
	v_cvt_pk_bf16_f32 v180, v176, v177
	v_cvt_pk_bf16_f32 v181, v178, v179
	global_store_dwordx2 v2, v[180:181], s[34:35]
	s_add_u32 s34, s34, 0x800
	s_addc_u32 s35, s35, 0
	s_waitcnt vmcnt(5)
; DEV unsigned pack2(float a, float b) { float2v v = {a, b}; return __builtin_bit_cast(unsigned, __builtin_convertvector(v, bf16x2v)); }
; DEV float bflo(unsigned u) { return __uint_as_float(u << 16); }
; DEV float bfhi(unsigned u) { return __uint_as_float(u & 0xffff0000u); }
; DEV float gelu_exact(float v) { return 0.5f * v * (1.f + erff(v * 0.7071067811865476f)); }
; DEV void ph_scan2(const Params& p, int item) {
;     ...
; #pragma unroll 8
;   for (int t = 0; t < CHL; ++t) {
;     float4 a = *(const float4*)(p.a_arr + (row0 + t) * 1024 + ch);
;     float4 bb = *(const float4*)(p.b_arr + (row0 + t) * 1024 + ch);
;     u32x2 xg = *(const u32x2*)(p.z + (row0 + t) * ZLD + CXG + ch);
;     H[0] = a.x * H[0] + bb.x; H[1] = a.y * H[1] + bb.y; H[2] = a.z * H[2] + bb.z; H[3] = a.w * H[3] + bb.w;
;     u32x2 pk;
;     pk[0] = pack2(gelu_exact(bflo(xg[0])) * H[0], gelu_exact(bfhi(xg[0])) * H[1]);
;     pk[1] = pack2(gelu_exact(bflo(xg[1])) * H[2], gelu_exact(bfhi(xg[1])) * H[3]);
;     *(u32x2*)(p.orn + (row0 + t) * 1024 + ch) = pk;
;   }
	v_fma_f32 v4, v100, v4, v104
	v_fma_f32 v5, v101, v5, v105
	v_fma_f32 v6, v102, v6, v106
	v_fma_f32 v7, v103, v7, v107
	v_lshlrev_b32_e32 v168, 16, v108
	v_and_b32_e32 v169, 0xffff0000, v108
	v_lshlrev_b32_e32 v170, 16, v109
	v_and_b32_e32 v171, 0xffff0000, v109
	v_mul_f32_e32 v160, 0x3f3504f3, v168
	v_mul_f32_e32 v161, v160, v160
	v_fmamk_f32 v162, v161, 0xba1345e1, v8
	v_fmaak_f32 v162, v161, v162, 0xbcdac9b8
	v_fmaak_f32 v162, v161, v162, 0x3de703be
	v_fmaak_f32 v162, v161, v162, 0xbec09330
	v_fmaak_f32 v161, v161, v162, 0x3e0375d0
	v_fma_f32 v165, |v160|, v161, |v160|
	v_fma_f32 v161, |v160|, s72, v9
	v_fma_f32 v161, |v160|, v161, s73
	v_fma_f32 v161, |v160|, v161, s74
	v_fma_f32 v161, |v160|, v161, s75
	v_fma_f32 v161, |v160|, v161, s76
	v_fma_f32 v161, |v160|, v161, s77
	v_fma_f32 v161, |v160|, v161, |v160|
	v_mul_f32_e32 v162, 0xbfb8aa3b, v161
	v_fma_f32 v163, v161, s78, -v162
	v_rndne_f32_e32 v164, v162
	v_fmac_f32_e32 v163, 0xb2a5705f, v161
	v_sub_f32_e32 v162, v162, v164
	v_add_f32_e32 v162, v162, v163
	v_cvt_i32_f32_e32 v163, v164
	v_exp_f32_e32 v162, v162
	v_cmp_nlt_f32_e32 vcc, s79, v161
	v_ldexp_f32 v162, v162, v163
	s_nop 0
	v_cndmask_b32_e32 v162, 0, v162, vcc
	v_cmp_ngt_f32_e32 vcc, s80, v161
	s_nop 1
	v_cndmask_b32_e32 v161, v3, v162, vcc
	v_sub_f32_e32 v166, 1.0, v161
	v_cmp_lt_f32_e64 vcc, |v160|, 1.0
	s_nop 1
	v_cndmask_b32_e32 v165, v166, v165, vcc
	v_bfi_b32 v165, s81, v165, v160
	v_mul_f32_e32 v161, 0.5, v168
	v_add_f32_e32 v165, 1.0, v165
	v_mul_f32_e32 v161, v161, v165
	v_mul_f32_e32 v176, v161, v4
	v_mul_f32_e32 v160, 0x3f3504f3, v169
	v_mul_f32_e32 v161, v160, v160
	v_fmamk_f32 v162, v161, 0xba1345e1, v8
	v_fmaak_f32 v162, v161, v162, 0xbcdac9b8
	v_fmaak_f32 v162, v161, v162, 0x3de703be
	v_fmaak_f32 v162, v161, v162, 0xbec09330
	v_fmaak_f32 v161, v161, v162, 0x3e0375d0
	v_fma_f32 v165, |v160|, v161, |v160|
	v_fma_f32 v161, |v160|, s72, v9
	v_fma_f32 v161, |v160|, v161, s73
	v_fma_f32 v161, |v160|, v161, s74
	v_fma_f32 v161, |v160|, v161, s75
	v_fma_f32 v161, |v160|, v161, s76
	v_fma_f32 v161, |v160|, v161, s77
	v_fma_f32 v161, |v160|, v161, |v160|
	v_mul_f32_e32 v162, 0xbfb8aa3b, v161
	v_fma_f32 v163, v161, s78, -v162
	v_rndne_f32_e32 v164, v162
	v_fmac_f32_e32 v163, 0xb2a5705f, v161
	v_sub_f32_e32 v162, v162, v164
	v_add_f32_e32 v162, v162, v163
	v_cvt_i32_f32_e32 v163, v164
	v_exp_f32_e32 v162, v162
	v_cmp_nlt_f32_e32 vcc, s79, v161
	v_ldexp_f32 v162, v162, v163
	s_nop 0
	v_cndmask_b32_e32 v162, 0, v162, vcc
	v_cmp_ngt_f32_e32 vcc, s80, v161
	s_nop 1
	v_cndmask_b32_e32 v161, v3, v162, vcc
	v_sub_f32_e32 v166, 1.0, v161
	v_cmp_lt_f32_e64 vcc, |v160|, 1.0
	s_nop 1
	v_cndmask_b32_e32 v165, v166, v165, vcc
	v_bfi_b32 v165, s81, v165, v160
	v_mul_f32_e32 v161, 0.5, v169
	v_add_f32_e32 v165, 1.0, v165
	v_mul_f32_e32 v161, v161, v165
	v_mul_f32_e32 v177, v161, v5
	v_mul_f32_e32 v160, 0x3f3504f3, v170
	v_mul_f32_e32 v161, v160, v160
	v_fmamk_f32 v162, v161, 0xba1345e1, v8
	v_fmaak_f32 v162, v161, v162, 0xbcdac9b8
	v_fmaak_f32 v162, v161, v162, 0x3de703be
	v_fmaak_f32 v162, v161, v162, 0xbec09330
	v_fmaak_f32 v161, v161, v162, 0x3e0375d0
	v_fma_f32 v165, |v160|, v161, |v160|
	v_fma_f32 v161, |v160|, s72, v9
	v_fma_f32 v161, |v160|, v161, s73
	v_fma_f32 v161, |v160|, v161, s74
	v_fma_f32 v161, |v160|, v161, s75
	v_fma_f32 v161, |v160|, v161, s76
	v_fma_f32 v161, |v160|, v161, s77
	v_fma_f32 v161, |v160|, v161, |v160|
	v_mul_f32_e32 v162, 0xbfb8aa3b, v161
	v_fma_f32 v163, v161, s78, -v162
	v_rndne_f32_e32 v164, v162
	v_fmac_f32_e32 v163, 0xb2a5705f, v161
	v_sub_f32_e32 v162, v162, v164
	v_add_f32_e32 v162, v162, v163
	v_cvt_i32_f32_e32 v163, v164
	v_exp_f32_e32 v162, v162
	v_cmp_nlt_f32_e32 vcc, s79, v161
	v_ldexp_f32 v162, v162, v163
	s_nop 0
	v_cndmask_b32_e32 v162, 0, v162, vcc
	v_cmp_ngt_f32_e32 vcc, s80, v161
	s_nop 1
	v_cndmask_b32_e32 v161, v3, v162, vcc
	v_sub_f32_e32 v166, 1.0, v161
	v_cmp_lt_f32_e64 vcc, |v160|, 1.0
	s_nop 1
	v_cndmask_b32_e32 v165, v166, v165, vcc
	v_bfi_b32 v165, s81, v165, v160
	v_mul_f32_e32 v161, 0.5, v170
	v_add_f32_e32 v165, 1.0, v165
	v_mul_f32_e32 v161, v161, v165
	v_mul_f32_e32 v178, v161, v6
	v_mul_f32_e32 v160, 0x3f3504f3, v171
	v_mul_f32_e32 v161, v160, v160
	v_fmamk_f32 v162, v161, 0xba1345e1, v8
	v_fmaak_f32 v162, v161, v162, 0xbcdac9b8
	v_fmaak_f32 v162, v161, v162, 0x3de703be
	v_fmaak_f32 v162, v161, v162, 0xbec09330
	v_fmaak_f32 v161, v161, v162, 0x3e0375d0
	v_fma_f32 v165, |v160|, v161, |v160|
	v_fma_f32 v161, |v160|, s72, v9
	v_fma_f32 v161, |v160|, v161, s73
	v_fma_f32 v161, |v160|, v161, s74
	v_fma_f32 v161, |v160|, v161, s75
	v_fma_f32 v161, |v160|, v161, s76
	v_fma_f32 v161, |v160|, v161, s77
	v_fma_f32 v161, |v160|, v161, |v160|
	v_mul_f32_e32 v162, 0xbfb8aa3b, v161
	v_fma_f32 v163, v161, s78, -v162
	v_rndne_f32_e32 v164, v162
	v_fmac_f32_e32 v163, 0xb2a5705f, v161
	v_sub_f32_e32 v162, v162, v164
	v_add_f32_e32 v162, v162, v163
	v_cvt_i32_f32_e32 v163, v164
	v_exp_f32_e32 v162, v162
	v_cmp_nlt_f32_e32 vcc, s79, v161
	v_ldexp_f32 v162, v162, v163
	s_nop 0
	v_cndmask_b32_e32 v162, 0, v162, vcc
	v_cmp_ngt_f32_e32 vcc, s80, v161
	s_nop 1
	v_cndmask_b32_e32 v161, v3, v162, vcc
	v_sub_f32_e32 v166, 1.0, v161
	v_cmp_lt_f32_e64 vcc, |v160|, 1.0
	s_nop 1
	v_cndmask_b32_e32 v165, v166, v165, vcc
	v_bfi_b32 v165, s81, v165, v160
	v_mul_f32_e32 v161, 0.5, v171
	v_add_f32_e32 v165, 1.0, v165
	v_mul_f32_e32 v161, v161, v165
	v_mul_f32_e32 v179, v161, v7
	v_cvt_pk_bf16_f32 v180, v176, v177
	v_cvt_pk_bf16_f32 v181, v178, v179
	global_store_dwordx2 v2, v[180:181], s[34:35]
	s_add_u32 s34, s34, 0x800
	s_addc_u32 s35, s35, 0
	s_waitcnt vmcnt(3)
; DEV unsigned pack2(float a, float b) { float2v v = {a, b}; return __builtin_bit_cast(unsigned, __builtin_convertvector(v, bf16x2v)); }
; DEV float bflo(unsigned u) { return __uint_as_float(u << 16); }
; DEV float bfhi(unsigned u) { return __uint_as_float(u & 0xffff0000u); }
; DEV float gelu_exact(float v) { return 0.5f * v * (1.f + erff(v * 0.7071067811865476f)); }
; DEV void ph_scan2(const Params& p, int item) {
;     ...
; #pragma unroll 8
;   for (int t = 0; t < CHL; ++t) {
;     float4 a = *(const float4*)(p.a_arr + (row0 + t) * 1024 + ch);
;     float4 bb = *(const float4*)(p.b_arr + (row0 + t) * 1024 + ch);
;     u32x2 xg = *(const u32x2*)(p.z + (row0 + t) * ZLD + CXG + ch);
;     H[0] = a.x * H[0] + bb.x; H[1] = a.y * H[1] + bb.y; H[2] = a.z * H[2] + bb.z; H[3] = a.w * H[3] + bb.w;
;     u32x2 pk;
;     pk[0] = pack2(gelu_exact(bflo(xg[0])) * H[0], gelu_exact(bfhi(xg[0])) * H[1]);
;     pk[1] = pack2(gelu_exact(bflo(xg[1])) * H[2], gelu_exact(bfhi(xg[1])) * H[3]);
;     *(u32x2*)(p.orn + (row0 + t) * 1024 + ch) = pk;
;   }
	v_fma_f32 v4, v110, v4, v114
	v_fma_f32 v5, v111, v5, v115
	v_fma_f32 v6, v112, v6, v116
	v_fma_f32 v7, v113, v7, v117
	v_lshlrev_b32_e32 v168, 16, v118
	v_and_b32_e32 v169, 0xffff0000, v118
	v_lshlrev_b32_e32 v170, 16, v119
	v_and_b32_e32 v171, 0xffff0000, v119
	v_mul_f32_e32 v160, 0x3f3504f3, v168
	v_mul_f32_e32 v161, v160, v160
	v_fmamk_f32 v162, v161, 0xba1345e1, v8
	v_fmaak_f32 v162, v161, v162, 0xbcdac9b8
	v_fmaak_f32 v162, v161, v162, 0x3de703be
	v_fmaak_f32 v162, v161, v162, 0xbec09330
	v_fmaak_f32 v161, v161, v162, 0x3e0375d0
	v_fma_f32 v165, |v160|, v161, |v160|
	v_fma_f32 v161, |v160|, s72, v9
	v_fma_f32 v161, |v160|, v161, s73
	v_fma_f32 v161, |v160|, v161, s74
	v_fma_f32 v161, |v160|, v161, s75
	v_fma_f32 v161, |v160|, v161, s76
	v_fma_f32 v161, |v160|, v161, s77
	v_fma_f32 v161, |v160|, v161, |v160|
	v_mul_f32_e32 v162, 0xbfb8aa3b, v161
	v_fma_f32 v163, v161, s78, -v162
	v_rndne_f32_e32 v164, v162
	v_fmac_f32_e32 v163, 0xb2a5705f, v161
	v_sub_f32_e32 v162, v162, v164
	v_add_f32_e32 v162, v162, v163
	v_cvt_i32_f32_e32 v163, v164
	v_exp_f32_e32 v162, v162
	v_cmp_nlt_f32_e32 vcc, s79, v161
	v_ldexp_f32 v162, v162, v163
	s_nop 0
	v_cndmask_b32_e32 v162, 0, v162, vcc
	v_cmp_ngt_f32_e32 vcc, s80, v161
	s_nop 1
	v_cndmask_b32_e32 v161, v3, v162, vcc
	v_sub_f32_e32 v166, 1.0, v161
	v_cmp_lt_f32_e64 vcc, |v160|, 1.0
	s_nop 1
	v_cndmask_b32_e32 v165, v166, v165, vcc
	v_bfi_b32 v165, s81, v165, v160
	v_mul_f32_e32 v161, 0.5, v168
	v_add_f32_e32 v165, 1.0, v165
	v_mul_f32_e32 v161, v161, v165
	v_mul_f32_e32 v176, v161, v4
	v_mul_f32_e32 v160, 0x3f3504f3, v169
	v_mul_f32_e32 v161, v160, v160
	v_fmamk_f32 v162, v161, 0xba1345e1, v8
	v_fmaak_f32 v162, v161, v162, 0xbcdac9b8
	v_fmaak_f32 v162, v161, v162, 0x3de703be
	v_fmaak_f32 v162, v161, v162, 0xbec09330
	v_fmaak_f32 v161, v161, v162, 0x3e0375d0
	v_fma_f32 v165, |v160|, v161, |v160|
	v_fma_f32 v161, |v160|, s72, v9
	v_fma_f32 v161, |v160|, v161, s73
	v_fma_f32 v161, |v160|, v161, s74
	v_fma_f32 v161, |v160|, v161, s75
	v_fma_f32 v161, |v160|, v161, s76
	v_fma_f32 v161, |v160|, v161, s77
	v_fma_f32 v161, |v160|, v161, |v160|
	v_mul_f32_e32 v162, 0xbfb8aa3b, v161
	v_fma_f32 v163, v161, s78, -v162
	v_rndne_f32_e32 v164, v162
	v_fmac_f32_e32 v163, 0xb2a5705f, v161
	v_sub_f32_e32 v162, v162, v164
	v_add_f32_e32 v162, v162, v163
	v_cvt_i32_f32_e32 v163, v164
	v_exp_f32_e32 v162, v162
	v_cmp_nlt_f32_e32 vcc, s79, v161
	v_ldexp_f32 v162, v162, v163
	s_nop 0
	v_cndmask_b32_e32 v162, 0, v162, vcc
	v_cmp_ngt_f32_e32 vcc, s80, v161
	s_nop 1
	v_cndmask_b32_e32 v161, v3, v162, vcc
	v_sub_f32_e32 v166, 1.0, v161
	v_cmp_lt_f32_e64 vcc, |v160|, 1.0
	s_nop 1
	v_cndmask_b32_e32 v165, v166, v165, vcc
	v_bfi_b32 v165, s81, v165, v160
	v_mul_f32_e32 v161, 0.5, v169
	v_add_f32_e32 v165, 1.0, v165
	v_mul_f32_e32 v161, v161, v165
	v_mul_f32_e32 v177, v161, v5
	v_mul_f32_e32 v160, 0x3f3504f3, v170
	v_mul_f32_e32 v161, v160, v160
	v_fmamk_f32 v162, v161, 0xba1345e1, v8
	v_fmaak_f32 v162, v161, v162, 0xbcdac9b8
	v_fmaak_f32 v162, v161, v162, 0x3de703be
	v_fmaak_f32 v162, v161, v162, 0xbec09330
	v_fmaak_f32 v161, v161, v162, 0x3e0375d0
	v_fma_f32 v165, |v160|, v161, |v160|
	v_fma_f32 v161, |v160|, s72, v9
	v_fma_f32 v161, |v160|, v161, s73
	v_fma_f32 v161, |v160|, v161, s74
	v_fma_f32 v161, |v160|, v161, s75
	v_fma_f32 v161, |v160|, v161, s76
	v_fma_f32 v161, |v160|, v161, s77
	v_fma_f32 v161, |v160|, v161, |v160|
	v_mul_f32_e32 v162, 0xbfb8aa3b, v161
	v_fma_f32 v163, v161, s78, -v162
	v_rndne_f32_e32 v164, v162
	v_fmac_f32_e32 v163, 0xb2a5705f, v161
	v_sub_f32_e32 v162, v162, v164
	v_add_f32_e32 v162, v162, v163
	v_cvt_i32_f32_e32 v163, v164
	v_exp_f32_e32 v162, v162
	v_cmp_nlt_f32_e32 vcc, s79, v161
	v_ldexp_f32 v162, v162, v163
	s_nop 0
	v_cndmask_b32_e32 v162, 0, v162, vcc
	v_cmp_ngt_f32_e32 vcc, s80, v161
	s_nop 1
	v_cndmask_b32_e32 v161, v3, v162, vcc
	v_sub_f32_e32 v166, 1.0, v161
	v_cmp_lt_f32_e64 vcc, |v160|, 1.0
	s_nop 1
	v_cndmask_b32_e32 v165, v166, v165, vcc
	v_bfi_b32 v165, s81, v165, v160
	v_mul_f32_e32 v161, 0.5, v170
	v_add_f32_e32 v165, 1.0, v165
	v_mul_f32_e32 v161, v161, v165
	v_mul_f32_e32 v178, v161, v6
	v_mul_f32_e32 v160, 0x3f3504f3, v171
	v_mul_f32_e32 v161, v160, v160
	v_fmamk_f32 v162, v161, 0xba1345e1, v8
	v_fmaak_f32 v162, v161, v162, 0xbcdac9b8
	v_fmaak_f32 v162, v161, v162, 0x3de703be
	v_fmaak_f32 v162, v161, v162, 0xbec09330
	v_fmaak_f32 v161, v161, v162, 0x3e0375d0
	v_fma_f32 v165, |v160|, v161, |v160|
	v_fma_f32 v161, |v160|, s72, v9
	v_fma_f32 v161, |v160|, v161, s73
	v_fma_f32 v161, |v160|, v161, s74
	v_fma_f32 v161, |v160|, v161, s75
	v_fma_f32 v161, |v160|, v161, s76
	v_fma_f32 v161, |v160|, v161, s77
	v_fma_f32 v161, |v160|, v161, |v160|
	v_mul_f32_e32 v162, 0xbfb8aa3b, v161
	v_fma_f32 v163, v161, s78, -v162
	v_rndne_f32_e32 v164, v162
	v_fmac_f32_e32 v163, 0xb2a5705f, v161
	v_sub_f32_e32 v162, v162, v164
	v_add_f32_e32 v162, v162, v163
	v_cvt_i32_f32_e32 v163, v164
	v_exp_f32_e32 v162, v162
	v_cmp_nlt_f32_e32 vcc, s79, v161
	v_ldexp_f32 v162, v162, v163
	s_nop 0
	v_cndmask_b32_e32 v162, 0, v162, vcc
	v_cmp_ngt_f32_e32 vcc, s80, v161
	s_nop 1
	v_cndmask_b32_e32 v161, v3, v162, vcc
	v_sub_f32_e32 v166, 1.0, v161
	v_cmp_lt_f32_e64 vcc, |v160|, 1.0
	s_nop 1
	v_cndmask_b32_e32 v165, v166, v165, vcc
	v_bfi_b32 v165, s81, v165, v160
	v_mul_f32_e32 v161, 0.5, v171
	v_add_f32_e32 v165, 1.0, v165
	v_mul_f32_e32 v161, v161, v165
	v_mul_f32_e32 v179, v161, v7
	v_cvt_pk_bf16_f32 v180, v176, v177
	v_cvt_pk_bf16_f32 v181, v178, v179
	global_store_dwordx2 v2, v[180:181], s[34:35]
	s_add_u32 s34, s34, 0x800
	s_addc_u32 s35, s35, 0
	s_add_u32 s41, s41, 1
	s_cmp_lt_u32 s41, 8
	s_cbranch_scc1 .Lsc_main
	s_add_i32 s50, s50, s92
	s_cmpk_lt_i32 s50, 0x200
	s_cbranch_scc1 .Lsc_item
	v_readlane_b32 s2, v254, 0
	s_nop 3
	s_cmp_lt_u32 s2, 0x100
	s_cbranch_scc1 .Lp5_resume
